# NSA pipelining v3: four of the eight next-tile QK MFMAs inside the row-max chain, remaining four earlier in the exp section (same as base_M otherwise)
# speedup vs baseline: 1.0006x; 1.0006x over previous
; #define LAS __attribute__((address_space(3)))
; #define MFMA32(a, b, c) __builtin_amdgcn_mfma_f32_32x32x16_bf16((a), (b), (c), 0, 0, 0)
; DI float fexp2(float x) { return __builtin_amdgcn_exp2f(x); }
; DI float half_max(float v) { return fmaxf(v, __shfl_xor(v, 32)); }
; DI void flash_qk(const LAS unsigned char* kb, const bf16x8 (&qf)[4], f32x16& p0, f32x16& p1, int r32, int h) {
;     ...
;     for (int s = 0; s < 4; ++s) {
;         const int off = r32 * 128 + (((2 * s + h) ^ sw) << 4);
;         const bf16x8 a0 = *(const LAS bf16x8*)(kb + off), a1 = *(const LAS bf16x8*)(kb + off + 4096);
;         p0 = MFMA32(a0, qf[s], p0); p1 = MFMA32(a1, qf[s], p1);
;     }
; DI void flash_pv(FState& st, f32x16& p0, f32x16& p1, bool rowon, const LAS unsigned char* vb, int lane) {
;     float mx = fmaxf(p0[0], p1[0]);
; #pragma unroll
;     for (int r = 1; r < 16; ++r) asm("v_max3_f32 %0, %1, %2, %3" : "=v"(mx) : "v"(mx), "v"(p0[r]), "v"(p1[r]));
;     mx = half_max(mx);
;     mx = rowon ? mx : NINF;
;     const bool upd = mx > st.m + THR_RAW;
;     if (__any(upd)) {
;         const float mn = upd ? mx : st.m;
;         const float alpha = upd ? fexp2((st.m - mn) * SM_C) : 1.0f;
;         st.m = mn; st.l *= alpha;
; #pragma unroll
;         for (int r = 0; r < 16; ++r) { st.o0[r] *= alpha; st.o1[r] *= alpha; }
;     }
.LBB0_753:
	v_max_f32_e32 v2, v82, v82
	v_max_f32_e32 v4, v98, v98
	v_max_f32_e32 v2, v4, v2
	s_waitcnt lgkmcnt(3)
	v_mfma_f32_32x32x16_bf16 v[130:145], v[226:229], v[146:149], 0
	v_max3_f32 v2, v2, v99, v83
	v_and_b32_e32 v5, 64, v198
	v_max3_f32 v2, v2, v100, v84
	v_xor_b32_e32 v4, 32, v198
	s_waitcnt lgkmcnt(2)
	v_mfma_f32_32x32x16_bf16 v[114:129], v[230:233], v[146:149], 0
	ds_read_b128 v[226:229], v223 offset:16384
	ds_read_b128 v[230:233], v223 offset:20480
	v_max3_f32 v2, v2, v101, v85
	v_add_u32_e32 v5, 64, v5
	v_max3_f32 v2, v2, v102, v86
	v_cmp_lt_i32_e32 vcc, v4, v5
	s_waitcnt lgkmcnt(3)
	v_mfma_f32_32x32x16_bf16 v[130:145], v[234:237], v[150:153], v[130:145]
	v_max3_f32 v2, v2, v103, v87
	v_max3_f32 v2, v2, v104, v88
	v_max3_f32 v2, v2, v105, v89
	v_cndmask_b32_e32 v4, v198, v4, vcc
	s_waitcnt lgkmcnt(2)
	v_mfma_f32_32x32x16_bf16 v[114:129], v[238:241], v[150:153], v[114:129]
	ds_read_b128 v[234:237], v224 offset:16384
	ds_read_b128 v[238:241], v224 offset:20480
	v_max3_f32 v2, v2, v106, v90
	v_lshlrev_b32_e32 v215, 2, v4
	v_max3_f32 v2, v2, v107, v91
	v_max3_f32 v2, v2, v108, v92
	v_max3_f32 v2, v2, v109, v93
	v_max3_f32 v2, v2, v110, v94
	v_max3_f32 v2, v2, v111, v95
	v_max3_f32 v2, v2, v112, v96
	v_max3_f32 v2, v2, v113, v97
	v_mov_b32_e32 v4, v2
	s_nop 1
	v_permlane32_swap_b32_e32 v4, v2
	s_nop 0
	v_max_f32_e32 v2, v2, v4
	v_cndmask_b32_e64 v2, v186, v2, s[8:9]
	v_add_f32_e32 v4, 0x42317218, v216
	v_cmp_gt_f32_e32 vcc, v2, v4
	s_cbranch_vccz .LBB0_755
	s_nop 0
	v_cndmask_b32_e32 v4, v216, v2, vcc
	v_sub_f32_e32 v2, v216, v4
	v_mul_f32_e32 v2, 0x3e38aa3b, v2
	v_exp_f32_e32 v2, v2
	v_mov_b32_e32 v216, v4
	v_cndmask_b32_e32 v2, 1.0, v2, vcc
	v_mul_f32_e32 v214, v214, v2
	v_pk_mul_f32 v[80:81], v[80:81], v[2:3] op_sel_hi:[1,0]
	v_pk_mul_f32 v[78:79], v[78:79], v[2:3] op_sel_hi:[1,0]
	v_pk_mul_f32 v[76:77], v[76:77], v[2:3] op_sel_hi:[1,0]
	v_pk_mul_f32 v[74:75], v[74:75], v[2:3] op_sel_hi:[1,0]
	v_pk_mul_f32 v[72:73], v[72:73], v[2:3] op_sel_hi:[1,0]
	v_pk_mul_f32 v[70:71], v[70:71], v[2:3] op_sel_hi:[1,0]
	v_pk_mul_f32 v[68:69], v[68:69], v[2:3] op_sel_hi:[1,0]
	v_pk_mul_f32 v[66:67], v[66:67], v[2:3] op_sel_hi:[1,0]
	v_pk_mul_f32 v[64:65], v[64:65], v[2:3] op_sel_hi:[1,0]
	v_pk_mul_f32 v[62:63], v[62:63], v[2:3] op_sel_hi:[1,0]
	v_pk_mul_f32 v[60:61], v[60:61], v[2:3] op_sel_hi:[1,0]
	v_pk_mul_f32 v[58:59], v[58:59], v[2:3] op_sel_hi:[1,0]
	v_pk_mul_f32 v[56:57], v[56:57], v[2:3] op_sel_hi:[1,0]
	v_pk_mul_f32 v[54:55], v[54:55], v[2:3] op_sel_hi:[1,0]
	v_pk_mul_f32 v[52:53], v[52:53], v[2:3] op_sel_hi:[1,0]
	v_pk_mul_f32 v[50:51], v[50:51], v[2:3] op_sel_hi:[1,0]

; #define LAS __attribute__((address_space(3)))
; #define MFMA32(a, b, c) __builtin_amdgcn_mfma_f32_32x32x16_bf16((a), (b), (c), 0, 0, 0)
; DI float fexp2(float x) { return __builtin_amdgcn_exp2f(x); }
; DI s16x4 vtr(const LAS unsigned char* p) { return __builtin_bit_cast(s16x4, __builtin_amdgcn_ds_read_tr16_b64_v4i16((LAS v4i16_t*)p)); }
; DI void flash_pv(FState& st, f32x16& p0, f32x16& p1, bool rowon, const LAS unsigned char* vb, int lane) {
;     ...
;     const float cl = rowon ? SM_C : 0.0f;
;     const float bl = rowon ? ((st.m == NINF) ? 0.0f : -st.m * SM_C) : NINF;
;     float sum = 0.f;
; #pragma unroll
;     for (int r = 0; r < 16; ++r) { p0[r] = fexp2(__builtin_fmaf(p0[r], cl, bl)); p1[r] = fexp2(__builtin_fmaf(p1[r], cl, bl)); sum += p0[r] + p1[r]; }
;     st.l += sum;
;     const int h = lane >> 5;
;     const int vx = (((lane & 15) >> 3) & 1) * 64;
;     const LAS unsigned char* vp = vb + (4 * h + ((lane & 15) >> 2)) * 128 + ((lane >> 4) & 1) * 32 + (lane & 3) * 8;
; #pragma unroll
;     for (int sub = 0; sub < 2; ++sub)
; #pragma unroll
;         for (int s2 = 0; s2 < 2; ++s2) {
;             const bf16x8 pf = pack8h(sub ? p1 : p0, s2);
;             const LAS unsigned char* vq = vp + (32 * sub + 16 * s2) * 128;
;             { const s16x4 lo = vtr(vq + vx), hi = vtr(vq + 1024 + vx); const bf16x8 vf = {lo[0], lo[1], lo[2], lo[3], hi[0], hi[1], hi[2], hi[3]}; st.o0 = MFMA32(vf, pf, st.o0); }
;             { const s16x4 lo = vtr(vq + (64 - vx)), hi = vtr(vq + 1024 + (64 - vx)); const bf16x8 vf = {lo[0], lo[1], lo[2], lo[3], hi[0], hi[1], hi[2], hi[3]}; st.o1 = MFMA32(vf, pf, st.o1); }
;         }
.LBB0_759:
	s_or_b64 exec, exec, s[4:5]
	v_fma_f32 v2, v98, v5, v4
	v_exp_f32_e32 v12, v2
	v_fma_f32 v2, v82, v5, v4
	v_exp_f32_e32 v246, v2
	s_waitcnt lgkmcnt(3)
	v_mfma_f32_32x32x16_bf16 v[130:145], v[226:229], v[154:157], v[130:145]
	v_fma_f32 v2, v99, v5, v4
	v_exp_f32_e32 v6, v2
	v_fma_f32 v2, v83, v5, v4
	v_exp_f32_e32 v2, v2
	v_add_f32_e32 v7, v12, v246
	s_add_i32 s77, s74, 1
	s_cmp_ge_u32 s77, s51
	v_pk_add_f32 v[8:9], v[6:7], v[2:3]
	v_fma_f32 v7, v100, v5, v4
	v_pk_add_f32 v[98:99], v[8:9], v[8:9] op_sel_hi:[0,1]
	s_waitcnt lgkmcnt(2)
	v_mfma_f32_32x32x16_bf16 v[114:129], v[230:233], v[154:157], v[114:129]
	v_fma_f32 v8, v84, v5, v4
	v_exp_f32_e32 v7, v7
	v_exp_f32_e32 v247, v8
	v_fma_f32 v8, v101, v5, v4
	v_fma_f32 v9, v85, v5, v4
	v_exp_f32_e32 v8, v8
	v_exp_f32_e32 v98, v9
	v_add_f32_e32 v9, v7, v247
	v_cvt_pk_bf16_f32 v6, v12, v6
	v_cvt_pk_bf16_f32 v7, v7, v8
	s_waitcnt lgkmcnt(1)
	v_mfma_f32_32x32x16_bf16 v[130:145], v[234:237], v[158:161], v[130:145]
	v_pk_add_f32 v[10:11], v[8:9], v[98:99]
	v_fma_f32 v9, v102, v5, v4
	v_pk_add_f32 v[100:101], v[10:11], v[10:11] op_sel_hi:[0,1]
	v_fma_f32 v10, v86, v5, v4
	v_exp_f32_e32 v99, v10
	v_fma_f32 v10, v103, v5, v4
	v_exp_f32_e32 v9, v9
	v_exp_f32_e32 v14, v10
	v_fma_f32 v10, v87, v5, v4
	v_exp_f32_e32 v100, v10
	s_waitcnt lgkmcnt(0)
	v_mfma_f32_32x32x16_bf16 v[114:129], v[238:241], v[158:161], v[114:129]
	v_add_f32_e32 v15, v9, v99
	v_cvt_pk_bf16_f32 v8, v9, v14
	v_pk_add_f32 v[10:11], v[14:15], v[100:101]
	s_nop 0
	v_pk_add_f32 v[86:87], v[10:11], v[10:11] op_sel_hi:[0,1]
	v_fma_f32 v10, v104, v5, v4
	v_exp_f32_e32 v15, v10
	v_fma_f32 v10, v88, v5, v4
	v_exp_f32_e32 v101, v10
	v_fma_f32 v10, v105, v5, v4
	v_exp_f32_e32 v16, v10
	v_fma_f32 v10, v89, v5, v4
	v_exp_f32_e32 v86, v10
	v_add_f32_e32 v17, v15, v101
	v_cvt_pk_bf16_f32 v9, v15, v16
	v_pk_add_f32 v[10:11], v[16:17], v[86:87]
	s_nop 0
	v_pk_add_f32 v[88:89], v[10:11], v[10:11] op_sel_hi:[0,1]
	v_fma_f32 v10, v106, v5, v4
	v_exp_f32_e32 v87, v10
	v_fma_f32 v10, v90, v5, v4
	v_exp_f32_e32 v248, v10
	v_fma_f32 v10, v107, v5, v4
	v_exp_f32_e32 v90, v10
	v_fma_f32 v10, v91, v5, v4
	v_exp_f32_e32 v88, v10
	v_fma_f32 v10, v108, v5, v4
	v_exp_f32_e32 v107, v10
	v_fma_f32 v10, v92, v5, v4
	v_add_f32_e32 v91, v87, v248
	v_exp_f32_e32 v108, v10
	v_pk_add_f32 v[10:11], v[90:91], v[88:89]
	v_fma_f32 v91, v112, v5, v4
	v_pk_add_f32 v[102:103], v[10:11], v[10:11] op_sel_hi:[0,1]
	v_fma_f32 v10, v109, v5, v4
	v_exp_f32_e32 v104, v10
	v_fma_f32 v10, v93, v5, v4
	v_exp_f32_e32 v102, v10
	v_add_u32_e32 v10, s76, v211
	v_add3_u32 v17, v10, v203, v204
	v_add_u32_e32 v218, v17, v202
	ds_read_b64_tr_b16 v[10:11], v218 offset:8192
	ds_read_b64_tr_b16 v[12:13], v218 offset:9216
	v_add_u32_e32 v217, v17, v213
	ds_read_b64_tr_b16 v[14:15], v217 offset:8256
	ds_read_b64_tr_b16 v[16:17], v217 offset:9280
	ds_read_b64_tr_b16 v[82:83], v218 offset:10240
	ds_read_b64_tr_b16 v[84:85], v218 offset:11264
	s_waitcnt lgkmcnt(4)
	v_mfma_f32_32x32x16_bf16 v[66:81], v[10:13], v[6:9], v[66:81]
	v_fma_f32 v10, v110, v5, v4
	v_exp_f32_e32 v89, v10
	v_fma_f32 v10, v111, v5, v4
	v_exp_f32_e32 v92, v10
	v_exp_f32_e32 v109, v91
	v_add_f32_e32 v105, v107, v108
	ds_read_b64_tr_b16 v[10:11], v217 offset:10304
	ds_read_b64_tr_b16 v[12:13], v217 offset:11328
	s_waitcnt lgkmcnt(4)
	v_mfma_f32_32x32x16_bf16 v[50:65], v[14:17], v[6:9], v[50:65]
	v_fma_f32 v6, v113, v5, v4
	v_exp_f32_e32 v106, v6
	v_cvt_pk_bf16_f32 v6, v87, v90
	v_cvt_pk_bf16_f32 v7, v107, v104
	v_cvt_pk_bf16_f32 v8, v89, v92
	v_cvt_pk_bf16_f32 v9, v109, v106
	v_pk_add_f32 v[14:15], v[104:105], v[102:103]
	s_waitcnt lgkmcnt(2)
	v_mfma_f32_32x32x16_bf16 v[66:81], v[82:85], v[6:9], v[66:81]
	v_add_f32_e64 v90, v14, v14
	v_add_f32_e64 v91, v14, v15
	v_fma_f32 v14, v94, v5, v4
	v_exp_f32_e32 v94, v14
	ds_read_b64_tr_b16 v[14:15], v218 offset:12288
	ds_read_b64_tr_b16 v[16:17], v218 offset:13312
	v_fma_f32 v82, v95, v5, v4
	v_exp_f32_e32 v90, v82
	v_add_f32_e32 v93, v89, v94
	s_waitcnt lgkmcnt(2)
	v_mfma_f32_32x32x16_bf16 v[50:65], v[10:13], v[6:9], v[50:65]
	v_cvt_pk_bf16_f32 v6, v246, v2
	v_cvt_pk_bf16_f32 v7, v247, v98
	v_cvt_pk_bf16_f32 v8, v99, v100
	v_cvt_pk_bf16_f32 v9, v101, v86
	ds_read_b64_tr_b16 v[10:11], v218 offset:14336
	ds_read_b64_tr_b16 v[12:13], v218 offset:15360
	v_pk_add_f32 v[82:83], v[92:93], v[90:91]
	v_fma_f32 v2, v96, v5, v4
	s_waitcnt lgkmcnt(2)
	v_mfma_f32_32x32x16_bf16 v[66:81], v[14:17], v[6:9], v[66:81]
	ds_read_b64_tr_b16 v[14:15], v217 offset:12352
	ds_read_b64_tr_b16 v[16:17], v217 offset:13376
	v_add_f32_e64 v86, v82, v82
	v_add_f32_e64 v87, v82, v83
	v_fmac_f32_e32 v4, v97, v5
	ds_read_b64_tr_b16 v[82:83], v217 offset:14400
	ds_read_b64_tr_b16 v[84:85], v217 offset:15424
	v_exp_f32_e32 v2, v2
	v_exp_f32_e32 v86, v4
	v_cvt_pk_bf16_f32 v4, v248, v88
	s_waitcnt lgkmcnt(2)
	v_mfma_f32_32x32x16_bf16 v[50:65], v[14:17], v[6:9], v[50:65]
	v_cvt_pk_bf16_f32 v5, v108, v102
	v_cvt_pk_bf16_f32 v6, v94, v90
	v_cvt_pk_bf16_f32 v7, v2, v86
	v_add_f32_e32 v107, v109, v2
	v_add_f32_e64 v8, v106, v86
	v_add_f32_e64 v9, v107, v87
	v_add_f32_e32 v2, v8, v9
	v_mfma_f32_32x32x16_bf16 v[66:81], v[10:13], v[4:7], v[66:81]
	v_add_f32_e32 v214, v214, v2
	s_waitcnt lgkmcnt(0)
	v_mfma_f32_32x32x16_bf16 v[50:65], v[82:85], v[4:7], v[50:65]
	s_cbranch_scc1 .LBB0_780
	s_movk_i32 s76, 0x4000
	s_add_i32 s4, s74, 5
	s_cmp_ge_u32 s4, s51
	s_waitcnt vmcnt(1)
	ds_write_b128 v205, v[182:185] offset:32768
	s_waitcnt vmcnt(0)
	ds_write_b128 v212, v[178:181] offset:40960
	s_waitcnt lgkmcnt(0)
	s_barrier
	s_cbranch_scc1 .LBB0_762
	s_cmp_gt_u32 s4, s69
	s_cselect_b64 s[8:9], -1, 0
	s_mov_b32 s5, s52
	s_and_b64 s[8:9], s[8:9], exec
	s_cselect_b32 s4, s5, s4
	s_cselect_b32 s16, 0x1000, s65
	s_cselect_b32 s8, s64, 0x500
	s_lshl_b32 s4, s4, 6
	s_mov_b32 s9, s17
	v_mad_i64_i32 v[4:5], s[4:5], s4, v199, v[192:193]
	v_lshl_add_u64 v[6:7], v[4:5], 0, s[8:9]
	v_lshl_add_u64 v[4:5], v[4:5], 0, s[16:17]
	global_load_dwordx4 v[182:185], v[6:7], off
	global_load_dwordx4 v[178:181], v[4:5], off

; #define LAS __attribute__((address_space(3)))
; #define MFMA32(a, b, c) __builtin_amdgcn_mfma_f32_32x32x16_bf16((a), (b), (c), 0, 0, 0)
; DI float fexp2(float x) { return __builtin_amdgcn_exp2f(x); }
; DI float half_max(float v) { return fmaxf(v, __shfl_xor(v, 32)); }
; DI void flash_qk(const LAS unsigned char* kb, const bf16x8 (&qf)[4], f32x16& p0, f32x16& p1, int r32, int h) {
;     ...
;     for (int s = 0; s < 4; ++s) {
;         const int off = r32 * 128 + (((2 * s + h) ^ sw) << 4);
;         const bf16x8 a0 = *(const LAS bf16x8*)(kb + off), a1 = *(const LAS bf16x8*)(kb + off + 4096);
;         p0 = MFMA32(a0, qf[s], p0); p1 = MFMA32(a1, qf[s], p1);
;     }
; DI void flash_pv(FState& st, f32x16& p0, f32x16& p1, bool rowon, const LAS unsigned char* vb, int lane) {
;     float mx = fmaxf(p0[0], p1[0]);
; #pragma unroll
;     for (int r = 1; r < 16; ++r) asm("v_max3_f32 %0, %1, %2, %3" : "=v"(mx) : "v"(mx), "v"(p0[r]), "v"(p1[r]));
;     mx = half_max(mx);
;     mx = rowon ? mx : NINF;
;     const bool upd = mx > st.m + THR_RAW;
;     if (__any(upd)) {
;         const float mn = upd ? mx : st.m;
;         const float alpha = upd ? fexp2((st.m - mn) * SM_C) : 1.0f;
;         st.m = mn; st.l *= alpha;
; #pragma unroll
;         for (int r = 0; r < 16; ++r) { st.o0[r] *= alpha; st.o1[r] *= alpha; }
;     }
.LBB0_772:
	v_max_f32_e32 v2, v82, v82
	v_max_f32_e32 v4, v98, v98
	v_max_f32_e32 v2, v4, v2
	s_waitcnt lgkmcnt(3)
	v_mfma_f32_32x32x16_bf16 v[130:145], v[226:229], v[146:149], 0
	v_max3_f32 v2, v2, v99, v83
	v_max3_f32 v2, v2, v100, v84
	v_max3_f32 v2, v2, v101, v85
	v_max3_f32 v2, v2, v102, v86
	s_waitcnt lgkmcnt(2)
	v_mfma_f32_32x32x16_bf16 v[114:129], v[230:233], v[146:149], 0
	ds_read_b128 v[226:229], v223 offset:32768
	ds_read_b128 v[230:233], v223 offset:36864
	v_max3_f32 v2, v2, v103, v87
	v_max3_f32 v2, v2, v104, v88
	v_max3_f32 v2, v2, v105, v89
	v_max3_f32 v2, v2, v106, v90
	s_waitcnt lgkmcnt(3)
	v_mfma_f32_32x32x16_bf16 v[130:145], v[234:237], v[150:153], v[130:145]
	v_max3_f32 v2, v2, v107, v91
	v_max3_f32 v2, v2, v108, v92
	v_max3_f32 v2, v2, v109, v93
	v_max3_f32 v2, v2, v110, v94
	s_waitcnt lgkmcnt(2)
	v_mfma_f32_32x32x16_bf16 v[114:129], v[238:241], v[150:153], v[114:129]
	ds_read_b128 v[234:237], v224 offset:32768
	ds_read_b128 v[238:241], v224 offset:36864
	v_max3_f32 v2, v2, v111, v95
	v_max3_f32 v2, v2, v112, v96
	v_max3_f32 v2, v2, v113, v97
	v_mov_b32_e32 v4, v2
	s_nop 1
	v_permlane32_swap_b32_e32 v4, v2
	s_nop 0
	v_max_f32_e32 v2, v2, v4
	v_cndmask_b32_e64 v2, v186, v2, s[8:9]
	v_add_f32_e32 v4, 0x42317218, v216
	v_cmp_gt_f32_e32 vcc, v2, v4
	s_cbranch_vccz .LBB0_774
	s_nop 0
	v_cndmask_b32_e32 v4, v216, v2, vcc
	v_sub_f32_e32 v2, v216, v4
	v_mul_f32_e32 v2, 0x3e38aa3b, v2
	v_exp_f32_e32 v2, v2
	v_mov_b32_e32 v216, v4
	v_cndmask_b32_e32 v2, 1.0, v2, vcc
	v_mul_f32_e32 v214, v214, v2
	v_pk_mul_f32 v[80:81], v[80:81], v[2:3] op_sel_hi:[1,0]
	v_pk_mul_f32 v[78:79], v[78:79], v[2:3] op_sel_hi:[1,0]
	v_pk_mul_f32 v[76:77], v[76:77], v[2:3] op_sel_hi:[1,0]
	v_pk_mul_f32 v[74:75], v[74:75], v[2:3] op_sel_hi:[1,0]
	v_pk_mul_f32 v[72:73], v[72:73], v[2:3] op_sel_hi:[1,0]
	v_pk_mul_f32 v[70:71], v[70:71], v[2:3] op_sel_hi:[1,0]
	v_pk_mul_f32 v[68:69], v[68:69], v[2:3] op_sel_hi:[1,0]
	v_pk_mul_f32 v[66:67], v[66:67], v[2:3] op_sel_hi:[1,0]
	v_pk_mul_f32 v[64:65], v[64:65], v[2:3] op_sel_hi:[1,0]
	v_pk_mul_f32 v[62:63], v[62:63], v[2:3] op_sel_hi:[1,0]
	v_pk_mul_f32 v[60:61], v[60:61], v[2:3] op_sel_hi:[1,0]
	v_pk_mul_f32 v[58:59], v[58:59], v[2:3] op_sel_hi:[1,0]
	v_pk_mul_f32 v[56:57], v[56:57], v[2:3] op_sel_hi:[1,0]
	v_pk_mul_f32 v[54:55], v[54:55], v[2:3] op_sel_hi:[1,0]
	v_pk_mul_f32 v[52:53], v[52:53], v[2:3] op_sel_hi:[1,0]
	v_pk_mul_f32 v[50:51], v[50:51], v[2:3] op_sel_hi:[1,0]

; #define LAS __attribute__((address_space(3)))
; #define MFMA32(a, b, c) __builtin_amdgcn_mfma_f32_32x32x16_bf16((a), (b), (c), 0, 0, 0)
; DI float fexp2(float x) { return __builtin_amdgcn_exp2f(x); }
; DI s16x4 vtr(const LAS unsigned char* p) { return __builtin_bit_cast(s16x4, __builtin_amdgcn_ds_read_tr16_b64_v4i16((LAS v4i16_t*)p)); }
; DI void flash_qk(const LAS unsigned char* kb, const bf16x8 (&qf)[4], f32x16& p0, f32x16& p1, int r32, int h) {
;     ...
;     for (int s = 0; s < 4; ++s) {
;         const int off = r32 * 128 + (((2 * s + h) ^ sw) << 4);
;         const bf16x8 a0 = *(const LAS bf16x8*)(kb + off), a1 = *(const LAS bf16x8*)(kb + off + 4096);
;         p0 = MFMA32(a0, qf[s], p0); p1 = MFMA32(a1, qf[s], p1);
;     }
; DI void flash_pv(FState& st, f32x16& p0, f32x16& p1, bool rowon, const LAS unsigned char* vb, int lane) {
;     ...
;     const float cl = rowon ? SM_C : 0.0f;
;     const float bl = rowon ? ((st.m == NINF) ? 0.0f : -st.m * SM_C) : NINF;
;     float sum = 0.f;
; #pragma unroll
;     for (int r = 0; r < 16; ++r) { p0[r] = fexp2(__builtin_fmaf(p0[r], cl, bl)); p1[r] = fexp2(__builtin_fmaf(p1[r], cl, bl)); sum += p0[r] + p1[r]; }
;     st.l += sum;
;     const int h = lane >> 5;
;     const int vx = (((lane & 15) >> 3) & 1) * 64;
;     const LAS unsigned char* vp = vb + (4 * h + ((lane & 15) >> 2)) * 128 + ((lane >> 4) & 1) * 32 + (lane & 3) * 8;
; #pragma unroll
;     for (int sub = 0; sub < 2; ++sub)
; #pragma unroll
;         for (int s2 = 0; s2 < 2; ++s2) {
;             const bf16x8 pf = pack8h(sub ? p1 : p0, s2);
;             const LAS unsigned char* vq = vp + (32 * sub + 16 * s2) * 128;
;             { const s16x4 lo = vtr(vq + vx), hi = vtr(vq + 1024 + vx); const bf16x8 vf = {lo[0], lo[1], lo[2], lo[3], hi[0], hi[1], hi[2], hi[3]}; st.o0 = MFMA32(vf, pf, st.o0); }
;             { const s16x4 lo = vtr(vq + (64 - vx)), hi = vtr(vq + 1024 + (64 - vx)); const bf16x8 vf = {lo[0], lo[1], lo[2], lo[3], hi[0], hi[1], hi[2], hi[3]}; st.o1 = MFMA32(vf, pf, st.o1); }
;         }
.LBB0_778:
	s_or_b64 exec, exec, s[4:5]
	v_fma_f32 v2, v98, v5, v4
	v_exp_f32_e32 v12, v2
	v_fma_f32 v2, v82, v5, v4
	v_exp_f32_e32 v246, v2
	s_waitcnt lgkmcnt(3)
	v_mfma_f32_32x32x16_bf16 v[130:145], v[226:229], v[154:157], v[130:145]
	v_fma_f32 v2, v99, v5, v4
	v_exp_f32_e32 v6, v2
	v_fma_f32 v2, v83, v5, v4
	v_exp_f32_e32 v2, v2
	v_add_f32_e32 v7, v12, v246
	v_pk_add_f32 v[8:9], v[6:7], v[2:3]
	s_nop 0
	v_pk_add_f32 v[98:99], v[8:9], v[8:9] op_sel_hi:[0,1]
	v_fma_f32 v7, v100, v5, v4
	v_fma_f32 v8, v84, v5, v4
	s_waitcnt lgkmcnt(2)
	v_mfma_f32_32x32x16_bf16 v[114:129], v[230:233], v[154:157], v[114:129]
	v_exp_f32_e32 v7, v7
	v_exp_f32_e32 v247, v8
	v_fma_f32 v8, v101, v5, v4
	v_fma_f32 v9, v85, v5, v4
	v_exp_f32_e32 v8, v8
	v_exp_f32_e32 v98, v9
	v_add_f32_e32 v9, v7, v247
	v_cvt_pk_bf16_f32 v6, v12, v6
	v_cvt_pk_bf16_f32 v7, v7, v8
	v_pk_add_f32 v[10:11], v[8:9], v[98:99]
	s_waitcnt lgkmcnt(1)
	v_mfma_f32_32x32x16_bf16 v[130:145], v[234:237], v[158:161], v[130:145]
	v_fma_f32 v9, v102, v5, v4
	v_pk_add_f32 v[100:101], v[10:11], v[10:11] op_sel_hi:[0,1]
	v_fma_f32 v10, v86, v5, v4
	v_exp_f32_e32 v99, v10
	v_fma_f32 v10, v103, v5, v4
	v_exp_f32_e32 v9, v9
	v_exp_f32_e32 v14, v10
	v_fma_f32 v10, v87, v5, v4
	v_exp_f32_e32 v100, v10
	v_add_f32_e32 v15, v9, v99
	s_waitcnt lgkmcnt(0)
	v_mfma_f32_32x32x16_bf16 v[114:129], v[238:241], v[158:161], v[114:129]
	v_cvt_pk_bf16_f32 v8, v9, v14
	v_pk_add_f32 v[10:11], v[14:15], v[100:101]
	s_nop 0
	v_pk_add_f32 v[86:87], v[10:11], v[10:11] op_sel_hi:[0,1]
	v_fma_f32 v10, v104, v5, v4
	v_exp_f32_e32 v15, v10
	v_fma_f32 v10, v88, v5, v4
	v_exp_f32_e32 v101, v10
	v_fma_f32 v10, v105, v5, v4
	v_exp_f32_e32 v16, v10
	v_fma_f32 v10, v89, v5, v4
	v_exp_f32_e32 v86, v10
	v_add_f32_e32 v17, v15, v101
	v_cvt_pk_bf16_f32 v9, v15, v16
	v_pk_add_f32 v[10:11], v[16:17], v[86:87]
	s_nop 0
	v_pk_add_f32 v[88:89], v[10:11], v[10:11] op_sel_hi:[0,1]
	v_fma_f32 v10, v106, v5, v4
	v_exp_f32_e32 v87, v10
	v_fma_f32 v10, v90, v5, v4
	v_exp_f32_e32 v248, v10
	v_fma_f32 v10, v107, v5, v4
	v_exp_f32_e32 v90, v10
	v_fma_f32 v10, v91, v5, v4
	v_exp_f32_e32 v88, v10
	v_fma_f32 v10, v108, v5, v4
	v_exp_f32_e32 v107, v10
	v_fma_f32 v10, v92, v5, v4
	v_add_f32_e32 v91, v87, v248
	v_exp_f32_e32 v108, v10
	v_pk_add_f32 v[10:11], v[90:91], v[88:89]
	v_fma_f32 v91, v112, v5, v4
	v_pk_add_f32 v[102:103], v[10:11], v[10:11] op_sel_hi:[0,1]
	v_fma_f32 v10, v109, v5, v4
	v_exp_f32_e32 v104, v10
	v_fma_f32 v10, v93, v5, v4
	v_exp_f32_e32 v102, v10
	v_add_u32_e32 v10, s76, v211
	v_add3_u32 v17, v10, v203, v204
	v_add_u32_e32 v89, v17, v202
	ds_read_b64_tr_b16 v[10:11], v89 offset:8192
	ds_read_b64_tr_b16 v[12:13], v89 offset:9216
	v_add_u32_e32 v109, v17, v213
	ds_read_b64_tr_b16 v[14:15], v109 offset:8256
	ds_read_b64_tr_b16 v[16:17], v109 offset:9280
	ds_read_b64_tr_b16 v[82:83], v89 offset:10240
	ds_read_b64_tr_b16 v[84:85], v89 offset:11264
	s_waitcnt lgkmcnt(4)
	v_mfma_f32_32x32x16_bf16 v[66:81], v[10:13], v[6:9], v[66:81]
	v_fma_f32 v10, v110, v5, v4
	v_exp_f32_e32 v93, v10
	v_fma_f32 v10, v111, v5, v4
	v_exp_f32_e32 v92, v10
	v_exp_f32_e32 v110, v91
	v_add_f32_e32 v105, v107, v108
	ds_read_b64_tr_b16 v[10:11], v109 offset:10304
	ds_read_b64_tr_b16 v[12:13], v109 offset:11328
	s_waitcnt lgkmcnt(4)
	v_mfma_f32_32x32x16_bf16 v[50:65], v[14:17], v[6:9], v[50:65]
	v_fma_f32 v6, v113, v5, v4
	v_exp_f32_e32 v106, v6
	v_cvt_pk_bf16_f32 v6, v87, v90
	v_cvt_pk_bf16_f32 v7, v107, v104
	v_cvt_pk_bf16_f32 v8, v93, v92
	v_cvt_pk_bf16_f32 v9, v110, v106
	v_pk_add_f32 v[14:15], v[104:105], v[102:103]
	s_waitcnt lgkmcnt(2)
	v_mfma_f32_32x32x16_bf16 v[66:81], v[82:85], v[6:9], v[66:81]
	v_add_f32_e64 v90, v14, v14
	v_add_f32_e64 v91, v14, v15
	v_fma_f32 v14, v94, v5, v4
	v_exp_f32_e32 v94, v14
	ds_read_b64_tr_b16 v[14:15], v89 offset:12288
	ds_read_b64_tr_b16 v[16:17], v89 offset:13312
	v_fma_f32 v82, v95, v5, v4
	v_exp_f32_e32 v90, v82
	v_add_f32_e32 v93, v93, v94
	s_waitcnt lgkmcnt(2)
	v_mfma_f32_32x32x16_bf16 v[50:65], v[10:13], v[6:9], v[50:65]
	v_cvt_pk_bf16_f32 v6, v246, v2
	v_cvt_pk_bf16_f32 v7, v247, v98
	v_cvt_pk_bf16_f32 v8, v99, v100
	v_cvt_pk_bf16_f32 v9, v101, v86
	ds_read_b64_tr_b16 v[10:11], v89 offset:14336
	ds_read_b64_tr_b16 v[12:13], v89 offset:15360
	v_pk_add_f32 v[82:83], v[92:93], v[90:91]
	v_fma_f32 v2, v96, v5, v4
	s_waitcnt lgkmcnt(2)
	v_mfma_f32_32x32x16_bf16 v[66:81], v[14:17], v[6:9], v[66:81]
	ds_read_b64_tr_b16 v[14:15], v109 offset:12352
	ds_read_b64_tr_b16 v[16:17], v109 offset:13376
	v_add_f32_e64 v86, v82, v82
	v_add_f32_e64 v87, v82, v83
	v_fmac_f32_e32 v4, v97, v5
	ds_read_b64_tr_b16 v[82:83], v109 offset:14400
	ds_read_b64_tr_b16 v[84:85], v109 offset:15424
	v_exp_f32_e32 v2, v2
	v_exp_f32_e32 v86, v4
	v_cvt_pk_bf16_f32 v4, v248, v88
	s_waitcnt lgkmcnt(2)
	v_mfma_f32_32x32x16_bf16 v[50:65], v[14:17], v[6:9], v[50:65]
	v_cvt_pk_bf16_f32 v5, v108, v102
	v_cvt_pk_bf16_f32 v6, v94, v90
	v_cvt_pk_bf16_f32 v7, v2, v86
	v_add_f32_e32 v107, v110, v2
	v_add_f32_e64 v8, v106, v86
	v_add_f32_e64 v9, v107, v87
	v_add_f32_e32 v2, v8, v9
	v_mfma_f32_32x32x16_bf16 v[66:81], v[10:13], v[4:7], v[66:81]
	v_add_f32_e32 v214, v214, v2
	s_waitcnt lgkmcnt(0)
	v_mfma_f32_32x32x16_bf16 v[50:65], v[82:85], v[4:7], v[50:65]
	s_add_i32 s76, s74, 2
	s_cmp_ge_u32 s76, s51
	s_cbranch_scc0 .LBB0_781

; #define LAS __attribute__((address_space(3)))
; #define MFMA32(a, b, c) __builtin_amdgcn_mfma_f32_32x32x16_bf16((a), (b), (c), 0, 0, 0)
; DI float fexp2(float x) { return __builtin_amdgcn_exp2f(x); }
; DI float half_max(float v) { return fmaxf(v, __shfl_xor(v, 32)); }
; DI void flash_qk(const LAS unsigned char* kb, const bf16x8 (&qf)[4], f32x16& p0, f32x16& p1, int r32, int h) {
;     ...
;     for (int s = 0; s < 4; ++s) {
;         const int off = r32 * 128 + (((2 * s + h) ^ sw) << 4);
;         const bf16x8 a0 = *(const LAS bf16x8*)(kb + off), a1 = *(const LAS bf16x8*)(kb + off + 4096);
;         p0 = MFMA32(a0, qf[s], p0); p1 = MFMA32(a1, qf[s], p1);
;     }
; DI void flash_pv(FState& st, f32x16& p0, f32x16& p1, bool rowon, const LAS unsigned char* vb, int lane) {
;     float mx = fmaxf(p0[0], p1[0]);
; #pragma unroll
;     for (int r = 1; r < 16; ++r) asm("v_max3_f32 %0, %1, %2, %3" : "=v"(mx) : "v"(mx), "v"(p0[r]), "v"(p1[r]));
;     mx = half_max(mx);
;     mx = rowon ? mx : NINF;
;     const bool upd = mx > st.m + THR_RAW;
;     if (__any(upd)) {
;         const float mn = upd ? mx : st.m;
;         const float alpha = upd ? fexp2((st.m - mn) * SM_C) : 1.0f;
;         st.m = mn; st.l *= alpha;
; #pragma unroll
;         for (int r = 0; r < 16; ++r) { st.o0[r] *= alpha; st.o1[r] *= alpha; }
;     }
.LBB0_793:
	v_max_f32_e32 v2, v82, v82
	v_max_f32_e32 v4, v98, v98
	v_max_f32_e32 v2, v4, v2
	s_waitcnt lgkmcnt(3)
	v_mfma_f32_32x32x16_bf16 v[130:145], v[226:229], v[146:149], 0
	v_max3_f32 v2, v2, v99, v83
	v_max3_f32 v2, v2, v100, v84
	v_max3_f32 v2, v2, v101, v85
	v_max3_f32 v2, v2, v102, v86
	s_waitcnt lgkmcnt(2)
	v_mfma_f32_32x32x16_bf16 v[114:129], v[230:233], v[146:149], 0
	ds_read_b128 v[226:229], v223
	ds_read_b128 v[230:233], v223 offset:4096
	v_max3_f32 v2, v2, v103, v87
	v_max3_f32 v2, v2, v104, v88
	v_max3_f32 v2, v2, v105, v89
	v_max3_f32 v2, v2, v106, v90
	s_waitcnt lgkmcnt(3)
	v_mfma_f32_32x32x16_bf16 v[130:145], v[234:237], v[150:153], v[130:145]
	v_max3_f32 v2, v2, v107, v91
	v_max3_f32 v2, v2, v108, v92
	v_max3_f32 v2, v2, v109, v93
	v_max3_f32 v2, v2, v110, v94
	s_waitcnt lgkmcnt(2)
	v_mfma_f32_32x32x16_bf16 v[114:129], v[238:241], v[150:153], v[114:129]
	ds_read_b128 v[234:237], v224
	ds_read_b128 v[238:241], v224 offset:4096
	v_max3_f32 v2, v2, v111, v95
	v_max3_f32 v2, v2, v112, v96
	v_max3_f32 v2, v2, v113, v97
	v_mov_b32_e32 v4, v2
	s_nop 1
	v_permlane32_swap_b32_e32 v4, v2
	s_nop 0
	v_max_f32_e32 v2, v2, v4
	v_cndmask_b32_e64 v2, v186, v2, s[8:9]
	v_add_f32_e32 v4, 0x42317218, v216
	v_cmp_gt_f32_e32 vcc, v2, v4
	s_cbranch_vccz .LBB0_795
	s_nop 0
	v_cndmask_b32_e32 v4, v216, v2, vcc
	v_sub_f32_e32 v2, v216, v4
	v_mul_f32_e32 v2, 0x3e38aa3b, v2
	v_exp_f32_e32 v2, v2
	v_mov_b32_e32 v216, v4
	v_cndmask_b32_e32 v2, 1.0, v2, vcc
	v_mul_f32_e32 v214, v214, v2
	v_pk_mul_f32 v[80:81], v[80:81], v[2:3] op_sel_hi:[1,0]
	v_pk_mul_f32 v[78:79], v[78:79], v[2:3] op_sel_hi:[1,0]
	v_pk_mul_f32 v[76:77], v[76:77], v[2:3] op_sel_hi:[1,0]
	v_pk_mul_f32 v[74:75], v[74:75], v[2:3] op_sel_hi:[1,0]
	v_pk_mul_f32 v[72:73], v[72:73], v[2:3] op_sel_hi:[1,0]
	v_pk_mul_f32 v[70:71], v[70:71], v[2:3] op_sel_hi:[1,0]
	v_pk_mul_f32 v[68:69], v[68:69], v[2:3] op_sel_hi:[1,0]
	v_pk_mul_f32 v[66:67], v[66:67], v[2:3] op_sel_hi:[1,0]
	v_pk_mul_f32 v[64:65], v[64:65], v[2:3] op_sel_hi:[1,0]
	v_pk_mul_f32 v[62:63], v[62:63], v[2:3] op_sel_hi:[1,0]
	v_pk_mul_f32 v[60:61], v[60:61], v[2:3] op_sel_hi:[1,0]
	v_pk_mul_f32 v[58:59], v[58:59], v[2:3] op_sel_hi:[1,0]
	v_pk_mul_f32 v[56:57], v[56:57], v[2:3] op_sel_hi:[1,0]
	v_pk_mul_f32 v[54:55], v[54:55], v[2:3] op_sel_hi:[1,0]
	v_pk_mul_f32 v[52:53], v[52:53], v[2:3] op_sel_hi:[1,0]
	v_pk_mul_f32 v[50:51], v[50:51], v[2:3] op_sel_hi:[1,0]

; #define LAS __attribute__((address_space(3)))
; #define MFMA32(a, b, c) __builtin_amdgcn_mfma_f32_32x32x16_bf16((a), (b), (c), 0, 0, 0)
; DI float fexp2(float x) { return __builtin_amdgcn_exp2f(x); }
; DI s16x4 vtr(const LAS unsigned char* p) { return __builtin_bit_cast(s16x4, __builtin_amdgcn_ds_read_tr16_b64_v4i16((LAS v4i16_t*)p)); }
; DI void flash_pv(FState& st, f32x16& p0, f32x16& p1, bool rowon, const LAS unsigned char* vb, int lane) {
;     ...
;     const float cl = rowon ? SM_C : 0.0f;
;     const float bl = rowon ? ((st.m == NINF) ? 0.0f : -st.m * SM_C) : NINF;
;     float sum = 0.f;
; #pragma unroll
;     for (int r = 0; r < 16; ++r) { p0[r] = fexp2(__builtin_fmaf(p0[r], cl, bl)); p1[r] = fexp2(__builtin_fmaf(p1[r], cl, bl)); sum += p0[r] + p1[r]; }
;     st.l += sum;
;     const int h = lane >> 5;
;     const int vx = (((lane & 15) >> 3) & 1) * 64;
;     const LAS unsigned char* vp = vb + (4 * h + ((lane & 15) >> 2)) * 128 + ((lane >> 4) & 1) * 32 + (lane & 3) * 8;
; #pragma unroll
;     for (int sub = 0; sub < 2; ++sub)
; #pragma unroll
;         for (int s2 = 0; s2 < 2; ++s2) {
;             const bf16x8 pf = pack8h(sub ? p1 : p0, s2);
;             const LAS unsigned char* vq = vp + (32 * sub + 16 * s2) * 128;
;             { const s16x4 lo = vtr(vq + vx), hi = vtr(vq + 1024 + vx); const bf16x8 vf = {lo[0], lo[1], lo[2], lo[3], hi[0], hi[1], hi[2], hi[3]}; st.o0 = MFMA32(vf, pf, st.o0); }
;             { const s16x4 lo = vtr(vq + (64 - vx)), hi = vtr(vq + 1024 + (64 - vx)); const bf16x8 vf = {lo[0], lo[1], lo[2], lo[3], hi[0], hi[1], hi[2], hi[3]}; st.o1 = MFMA32(vf, pf, st.o1); }
;         }
; DI void nsa_task(LAS unsigned char* lds, const bf16_t* Z, const unsigned* selm, const bf16_t* OCMP, bf16_t* YA, int b, int hk, int c, int tid, int wave, int lane) {
;     ...
;     for (int it0 = 0; it0 < ntot; it0 += 3) {
;         NSA_STEP(it0, kA, vA);
;         if (it0 + 1 < ntot) NSA_STEP(it0 + 1, kB, vB);
;         if (it0 + 2 < ntot) NSA_STEP(it0 + 2, kC, vC);
;     }
.LBB0_799:
	s_or_b64 exec, exec, s[4:5]
	v_fma_f32 v2, v98, v5, v4
	v_exp_f32_e32 v246, v2
	v_fma_f32 v2, v82, v5, v4
	v_exp_f32_e32 v247, v2
	s_waitcnt lgkmcnt(3)
	v_mfma_f32_32x32x16_bf16 v[130:145], v[226:229], v[154:157], v[130:145]
	v_fma_f32 v2, v99, v5, v4
	v_exp_f32_e32 v10, v2
	v_fma_f32 v2, v83, v5, v4
	v_exp_f32_e32 v2, v2
	v_add_f32_e32 v11, v246, v247
	v_pk_add_f32 v[6:7], v[10:11], v[2:3]
	s_nop 0
	v_pk_add_f32 v[98:99], v[6:7], v[6:7] op_sel_hi:[0,1]
	v_fma_f32 v6, v100, v5, v4
	v_exp_f32_e32 v11, v6
	s_waitcnt lgkmcnt(2)
	v_mfma_f32_32x32x16_bf16 v[114:129], v[230:233], v[154:157], v[114:129]
	v_fma_f32 v6, v84, v5, v4
	v_exp_f32_e32 v248, v6
	v_fma_f32 v6, v101, v5, v4
	v_exp_f32_e32 v12, v6
	v_fma_f32 v6, v85, v5, v4
	v_exp_f32_e32 v98, v6
	v_add_f32_e32 v13, v11, v248
	v_cvt_pk_bf16_f32 v10, v246, v10
	v_cvt_pk_bf16_f32 v11, v11, v12
	v_pk_add_f32 v[6:7], v[12:13], v[98:99]
	s_waitcnt lgkmcnt(1)
	v_mfma_f32_32x32x16_bf16 v[130:145], v[234:237], v[158:161], v[130:145]
	s_nop 0
	v_pk_add_f32 v[100:101], v[6:7], v[6:7] op_sel_hi:[0,1]
	v_fma_f32 v6, v102, v5, v4
	v_exp_f32_e32 v13, v6
	v_fma_f32 v6, v86, v5, v4
	v_exp_f32_e32 v99, v6
	v_fma_f32 v6, v103, v5, v4
	v_exp_f32_e32 v14, v6
	v_fma_f32 v6, v87, v5, v4
	v_exp_f32_e32 v100, v6
	s_waitcnt lgkmcnt(0)
	v_mfma_f32_32x32x16_bf16 v[114:129], v[238:241], v[158:161], v[114:129]
	v_add_f32_e32 v15, v13, v99
	v_cvt_pk_bf16_f32 v12, v13, v14
	v_pk_add_f32 v[6:7], v[14:15], v[100:101]
	s_nop 0
	v_pk_add_f32 v[86:87], v[6:7], v[6:7] op_sel_hi:[0,1]
	v_fma_f32 v6, v104, v5, v4
	v_exp_f32_e32 v15, v6
	v_fma_f32 v6, v88, v5, v4
	v_exp_f32_e32 v101, v6
	v_fma_f32 v6, v105, v5, v4
	v_exp_f32_e32 v16, v6
	v_fma_f32 v6, v89, v5, v4
	v_exp_f32_e32 v86, v6
	v_add_f32_e32 v17, v15, v101
	v_cvt_pk_bf16_f32 v13, v15, v16
	v_pk_add_f32 v[6:7], v[16:17], v[86:87]
	s_nop 0
	v_pk_add_f32 v[88:89], v[6:7], v[6:7] op_sel_hi:[0,1]
	v_fma_f32 v6, v106, v5, v4
	v_exp_f32_e32 v87, v6
	v_fma_f32 v6, v90, v5, v4
	v_exp_f32_e32 v249, v6
	v_fma_f32 v6, v107, v5, v4
	v_exp_f32_e32 v90, v6
	v_fma_f32 v6, v91, v5, v4
	v_exp_f32_e32 v88, v6
	v_fma_f32 v6, v108, v5, v4
	v_exp_f32_e32 v107, v6
	v_fma_f32 v6, v92, v5, v4
	v_add_f32_e32 v91, v87, v249
	v_exp_f32_e32 v108, v6
	v_pk_add_f32 v[6:7], v[90:91], v[88:89]
	v_fma_f32 v91, v112, v5, v4
	v_pk_add_f32 v[102:103], v[6:7], v[6:7] op_sel_hi:[0,1]
	v_fma_f32 v6, v109, v5, v4
	v_exp_f32_e32 v104, v6
	v_fma_f32 v6, v93, v5, v4
	v_exp_f32_e32 v102, v6
	ds_read_b64_tr_b16 v[6:7], v218 offset:40960
	ds_read_b64_tr_b16 v[8:9], v218 offset:41984
	ds_read_b64_tr_b16 v[14:15], v217 offset:41024
	ds_read_b64_tr_b16 v[16:17], v217 offset:42048
	ds_read_b64_tr_b16 v[82:83], v218 offset:43008
	ds_read_b64_tr_b16 v[84:85], v218 offset:44032
	s_waitcnt lgkmcnt(4)
	v_mfma_f32_32x32x16_bf16 v[66:81], v[6:9], v[10:13], v[66:81]
	v_fma_f32 v6, v110, v5, v4
	v_exp_f32_e32 v89, v6
	v_fma_f32 v6, v111, v5, v4
	v_exp_f32_e32 v92, v6
	v_exp_f32_e32 v109, v91
	v_add_f32_e32 v105, v107, v108
	ds_read_b64_tr_b16 v[6:7], v217 offset:43072
	ds_read_b64_tr_b16 v[8:9], v217 offset:44096
	s_waitcnt lgkmcnt(4)
	v_mfma_f32_32x32x16_bf16 v[50:65], v[14:17], v[10:13], v[50:65]
	v_fma_f32 v10, v113, v5, v4
	v_exp_f32_e32 v106, v10
	v_cvt_pk_bf16_f32 v10, v87, v90
	v_cvt_pk_bf16_f32 v11, v107, v104
	v_cvt_pk_bf16_f32 v12, v89, v92
	v_cvt_pk_bf16_f32 v13, v109, v106
	v_pk_add_f32 v[14:15], v[104:105], v[102:103]
	s_waitcnt lgkmcnt(2)
	v_mfma_f32_32x32x16_bf16 v[66:81], v[82:85], v[10:13], v[66:81]
	v_add_f32_e64 v90, v14, v14
	v_add_f32_e64 v91, v14, v15
	v_fma_f32 v14, v94, v5, v4
	v_exp_f32_e32 v94, v14
	ds_read_b64_tr_b16 v[14:15], v218 offset:45056
	ds_read_b64_tr_b16 v[16:17], v218 offset:46080
	v_fma_f32 v82, v95, v5, v4
	v_exp_f32_e32 v90, v82
	v_add_f32_e32 v93, v89, v94
	s_waitcnt lgkmcnt(2)
	v_mfma_f32_32x32x16_bf16 v[50:65], v[6:9], v[10:13], v[50:65]
	v_cvt_pk_bf16_f32 v6, v247, v2
	v_cvt_pk_bf16_f32 v7, v248, v98
	v_cvt_pk_bf16_f32 v8, v99, v100
	v_cvt_pk_bf16_f32 v9, v101, v86
	ds_read_b64_tr_b16 v[10:11], v218 offset:47104
	ds_read_b64_tr_b16 v[12:13], v218 offset:48128
	v_pk_add_f32 v[82:83], v[92:93], v[90:91]
	v_fma_f32 v2, v96, v5, v4
	s_waitcnt lgkmcnt(2)
	v_mfma_f32_32x32x16_bf16 v[66:81], v[14:17], v[6:9], v[66:81]
	ds_read_b64_tr_b16 v[14:15], v217 offset:45120
	ds_read_b64_tr_b16 v[16:17], v217 offset:46144
	v_add_f32_e64 v86, v82, v82
	v_add_f32_e64 v87, v82, v83
	v_fmac_f32_e32 v4, v97, v5
	ds_read_b64_tr_b16 v[82:83], v217 offset:47168
	ds_read_b64_tr_b16 v[84:85], v217 offset:48192
	v_exp_f32_e32 v2, v2
	v_exp_f32_e32 v86, v4
	v_cvt_pk_bf16_f32 v4, v249, v88
	s_waitcnt lgkmcnt(2)
	v_mfma_f32_32x32x16_bf16 v[50:65], v[14:17], v[6:9], v[50:65]
	v_cvt_pk_bf16_f32 v5, v108, v102
	v_cvt_pk_bf16_f32 v6, v94, v90
	v_cvt_pk_bf16_f32 v7, v2, v86
	v_add_f32_e32 v107, v109, v2
	v_add_f32_e64 v8, v106, v86
	v_add_f32_e64 v9, v107, v87
	v_add_f32_e32 v2, v8, v9
	v_mfma_f32_32x32x16_bf16 v[66:81], v[10:13], v[4:7], v[66:81]
	v_add_f32_e32 v214, v214, v2
	s_waitcnt lgkmcnt(0)
	v_mfma_f32_32x32x16_bf16 v[50:65], v[82:85], v[4:7], v[50:65]
	s_add_i32 s52, s52, -3
	s_andn2_b64 vcc, exec, s[6:7]
	s_add_i32 s53, s53, 0xc000
	s_cbranch_vccz .LBB0_712
